# SA(0,0) LDS-DMA stage moved phase2->phase3 in all three GEMM loops; grid barrier leader publishes before its acquire; B1 qkv epilogue hand-written
# baseline (speedup 1.0000x reference)
.LBB0_446:
	s_add_u32 s28, s0, 0xfffc0080
	s_addc_u32 s29, s1, -1
	s_add_i32 s52, 16, 0x10000
	s_cmp_eq_u32 s51, 12
	s_cselect_b32 s31, s3, s29
	s_cselect_b32 s30, s23, s28
	v_add_u32_e32 v3, s52, v175
	s_cselect_b32 s29, s21, s50
	s_cselect_b32 s28, s48, s49
	s_add_i32 s54, 16, 0x14000
	ds_read_b128 v[142:145], v3
	s_waitcnt lgkmcnt(0)
	ds_read_b128 v[146:149], v3 offset:1024
	ds_read_b128 v[150:153], v3 offset:2048
	ds_read_b128 v[154:157], v3 offset:3072
	v_add_u32_e32 v3, s54, v175
	ds_read_b128 v[158:161], v3
	ds_read_b128 v[162:165], v3 offset:1024
	ds_read_b128 v[166:169], v3 offset:2048
	ds_read_b128 v[170:173], v3 offset:3072
	v_lshl_add_u64 v[210:211], s[0:1], 0, v[138:139]
	s_add_i32 m0, s39, 0xc000
	ds_read_b128 v[178:181], v177
	ds_read_b128 v[182:185], v177 offset:1024
	ds_read_b128 v[186:189], v177 offset:2048
	ds_read_b128 v[190:193], v177 offset:3072
	ds_read_b128 v[194:197], v177 offset:4096
	ds_read_b128 v[198:201], v177 offset:5120
	ds_read_b128 v[202:205], v177 offset:6144
	ds_read_b128 v[206:209], v177 offset:7168
	global_load_lds_dwordx4 v[210:211], off
	v_lshl_add_u64 v[210:211], s[0:1], 0, v[140:141]
	s_add_i32 m0, s39, 0xe000
	s_nop 0
	global_load_lds_dwordx4 v[210:211], off
	s_waitcnt vmcnt(8)
	s_waitcnt lgkmcnt(0)
	s_barrier
	s_setprio 1
	s_waitcnt lgkmcnt(0)
	v_mfma_f32_16x16x32_bf16 v[128:131], v[142:145], v[178:181], v[128:131]
	v_mfma_f32_16x16x32_bf16 v[120:123], v[150:153], v[178:181], v[120:123]
	v_mfma_f32_16x16x32_bf16 v[112:115], v[142:145], v[186:189], v[112:115]
	v_mfma_f32_16x16x32_bf16 v[104:107], v[150:153], v[186:189], v[104:107]
	v_mfma_f32_16x16x32_bf16 v[96:99], v[142:145], v[194:197], v[96:99]
	v_mfma_f32_16x16x32_bf16 v[88:91], v[150:153], v[194:197], v[88:91]
	v_mfma_f32_16x16x32_bf16 v[80:83], v[142:145], v[202:205], v[80:83]
	v_mfma_f32_16x16x32_bf16 v[72:75], v[150:153], v[202:205], v[72:75]
	v_mfma_f32_16x16x32_bf16 v[128:131], v[146:149], v[182:185], v[128:131]
	v_mfma_f32_16x16x32_bf16 v[120:123], v[154:157], v[182:185], v[120:123]
	v_mfma_f32_16x16x32_bf16 v[112:115], v[146:149], v[190:193], v[112:115]
	v_mfma_f32_16x16x32_bf16 v[104:107], v[154:157], v[190:193], v[104:107]
	v_mfma_f32_16x16x32_bf16 v[96:99], v[146:149], v[198:201], v[96:99]
	v_mfma_f32_16x16x32_bf16 v[88:91], v[154:157], v[198:201], v[88:91]
	v_mfma_f32_16x16x32_bf16 v[80:83], v[146:149], v[206:209], v[80:83]
	v_mfma_f32_16x16x32_bf16 v[72:75], v[154:157], v[206:209], v[72:75]
	s_setprio 0
	s_setprio 1
	v_mfma_f32_16x16x32_bf16 v[124:127], v[158:161], v[178:181], v[124:127]
	v_mfma_f32_16x16x32_bf16 v[116:119], v[166:169], v[178:181], v[116:119]
	v_mfma_f32_16x16x32_bf16 v[108:111], v[158:161], v[186:189], v[108:111]
	v_mfma_f32_16x16x32_bf16 v[100:103], v[166:169], v[186:189], v[100:103]
	v_mfma_f32_16x16x32_bf16 v[92:95], v[158:161], v[194:197], v[92:95]
	v_mfma_f32_16x16x32_bf16 v[84:87], v[166:169], v[194:197], v[84:87]
	v_mfma_f32_16x16x32_bf16 v[76:79], v[158:161], v[202:205], v[76:79]
	v_mfma_f32_16x16x32_bf16 v[68:71], v[166:169], v[202:205], v[68:71]
	v_mfma_f32_16x16x32_bf16 v[124:127], v[162:165], v[182:185], v[124:127]
	v_mfma_f32_16x16x32_bf16 v[116:119], v[170:173], v[182:185], v[116:119]
	v_mfma_f32_16x16x32_bf16 v[108:111], v[162:165], v[190:193], v[108:111]
	v_mfma_f32_16x16x32_bf16 v[100:103], v[170:173], v[190:193], v[100:103]
	v_mfma_f32_16x16x32_bf16 v[92:95], v[162:165], v[198:201], v[92:95]
	v_mfma_f32_16x16x32_bf16 v[84:87], v[170:173], v[198:201], v[84:87]
	v_mfma_f32_16x16x32_bf16 v[76:79], v[162:165], v[206:209], v[76:79]
	v_mfma_f32_16x16x32_bf16 v[68:71], v[170:173], v[206:209], v[68:71]
	s_setprio 0
	s_barrier
	s_add_i32 s52, s52, s38
	v_lshl_add_u64 v[210:211], s[28:29], 0, v[134:135]
	s_mov_b32 m0, s52
	ds_read_b128 v[178:181], v177 offset:16384
	ds_read_b128 v[182:185], v177 offset:17408
	ds_read_b128 v[186:189], v177 offset:18432
	ds_read_b128 v[190:193], v177 offset:19456
	ds_read_b128 v[194:197], v177 offset:20480
	ds_read_b128 v[198:201], v177 offset:21504
	ds_read_b128 v[202:205], v177 offset:22528
	ds_read_b128 v[206:209], v177 offset:23552
	global_load_lds_dwordx4 v[210:211], off
	s_add_i32 m0, s52, 0x2000
	s_add_u32 s52, s28, 0x40000
	v_lshl_add_u64 v[212:213], s[28:29], 0, v[0:1]
	s_addc_u32 s53, s29, 0
	s_add_i32 s54, s54, s38
	global_load_lds_dwordx4 v[212:213], off
	v_lshl_add_u64 v[214:215], s[52:53], 0, v[134:135]
	s_mov_b32 m0, s54
	v_lshl_add_u64 v[216:217], s[30:31], 0, v[132:133]
	global_load_lds_dwordx4 v[214:215], off
	v_lshl_add_u64 v[214:215], s[52:53], 0, v[0:1]
	s_add_i32 m0, s54, 0x2000
	s_nop 0
	global_load_lds_dwordx4 v[214:215], off
	v_lshl_add_u64 v[214:215], s[30:31], 0, v[136:137]
	s_waitcnt vmcnt(6)
	s_waitcnt lgkmcnt(0)
	s_barrier
	s_setprio 1
	s_waitcnt lgkmcnt(0)
	v_mfma_f32_16x16x32_bf16 v[64:67], v[142:145], v[178:181], v[64:67]
	v_mfma_f32_16x16x32_bf16 v[56:59], v[150:153], v[178:181], v[56:59]
	v_mfma_f32_16x16x32_bf16 v[48:51], v[142:145], v[186:189], v[48:51]
	v_mfma_f32_16x16x32_bf16 v[40:43], v[150:153], v[186:189], v[40:43]
	v_mfma_f32_16x16x32_bf16 v[32:35], v[142:145], v[194:197], v[32:35]
	v_mfma_f32_16x16x32_bf16 v[24:27], v[150:153], v[194:197], v[24:27]
	v_mfma_f32_16x16x32_bf16 v[16:19], v[142:145], v[202:205], v[16:19]
	v_mfma_f32_16x16x32_bf16 v[8:11], v[150:153], v[202:205], v[8:11]
	v_mfma_f32_16x16x32_bf16 v[64:67], v[146:149], v[182:185], v[64:67]
	v_mfma_f32_16x16x32_bf16 v[56:59], v[154:157], v[182:185], v[56:59]
	v_mfma_f32_16x16x32_bf16 v[48:51], v[146:149], v[190:193], v[48:51]
	v_mfma_f32_16x16x32_bf16 v[40:43], v[154:157], v[190:193], v[40:43]
	v_mfma_f32_16x16x32_bf16 v[32:35], v[146:149], v[198:201], v[32:35]
	v_mfma_f32_16x16x32_bf16 v[24:27], v[154:157], v[198:201], v[24:27]
	v_mfma_f32_16x16x32_bf16 v[16:19], v[146:149], v[206:209], v[16:19]
	v_mfma_f32_16x16x32_bf16 v[8:11], v[154:157], v[206:209], v[8:11]
	s_setprio 0
	s_setprio 1
	v_mfma_f32_16x16x32_bf16 v[60:63], v[158:161], v[178:181], v[60:63]
	v_mfma_f32_16x16x32_bf16 v[52:55], v[166:169], v[178:181], v[52:55]
	v_mfma_f32_16x16x32_bf16 v[44:47], v[158:161], v[186:189], v[44:47]
	v_mfma_f32_16x16x32_bf16 v[36:39], v[166:169], v[186:189], v[36:39]
	v_mfma_f32_16x16x32_bf16 v[28:31], v[158:161], v[194:197], v[28:31]
	v_mfma_f32_16x16x32_bf16 v[20:23], v[166:169], v[194:197], v[20:23]
	v_mfma_f32_16x16x32_bf16 v[12:15], v[158:161], v[202:205], v[12:15]
	v_mfma_f32_16x16x32_bf16 v[4:7], v[166:169], v[202:205], v[4:7]
	v_mfma_f32_16x16x32_bf16 v[60:63], v[162:165], v[182:185], v[60:63]
	v_mfma_f32_16x16x32_bf16 v[52:55], v[170:173], v[182:185], v[52:55]
	v_mfma_f32_16x16x32_bf16 v[44:47], v[162:165], v[190:193], v[44:47]
	v_mfma_f32_16x16x32_bf16 v[36:39], v[170:173], v[190:193], v[36:39]
	v_mfma_f32_16x16x32_bf16 v[28:31], v[162:165], v[198:201], v[28:31]
	v_mfma_f32_16x16x32_bf16 v[20:23], v[170:173], v[198:201], v[20:23]
	v_mfma_f32_16x16x32_bf16 v[12:15], v[162:165], v[206:209], v[12:15]
	v_mfma_f32_16x16x32_bf16 v[4:7], v[170:173], v[206:209], v[4:7]
	s_setprio 0
	s_barrier
	s_add_i32 s52, 16, 0x18000
	v_add_u32_e32 v3, s52, v175
	s_add_i32 s53, 16, 0x1c000
	ds_read_b128 v[142:145], v3
	ds_read_b128 v[146:149], v3 offset:1024
	ds_read_b128 v[150:153], v3 offset:2048
	ds_read_b128 v[154:157], v3 offset:3072
	v_add_u32_e32 v3, s53, v175
	ds_read_b128 v[158:161], v3
	ds_read_b128 v[162:165], v3 offset:1024
	ds_read_b128 v[166:169], v3 offset:2048
	ds_read_b128 v[170:173], v3 offset:3072
	s_mov_b32 m0, s39
	s_nop 0
	global_load_lds_dwordx4 v[214:215], off
	s_mov_b32 m0, s40
	s_nop 0
	global_load_lds_dwordx4 v[216:217], off
	s_add_u32 s30, s30, 0x40000
	s_addc_u32 s31, s31, 0
	s_mov_b32 m0, s41
	v_lshl_add_u64 v[218:219], s[30:31], 0, v[136:137]
	ds_read_b128 v[178:181], v177 offset:32768
	ds_read_b128 v[182:185], v177 offset:33792
	ds_read_b128 v[186:189], v177 offset:34816
	ds_read_b128 v[190:193], v177 offset:35840
	ds_read_b128 v[194:197], v177 offset:36864
	ds_read_b128 v[198:201], v177 offset:37888
	ds_read_b128 v[202:205], v177 offset:38912
	ds_read_b128 v[206:209], v177 offset:39936
	global_load_lds_dwordx4 v[218:219], off
	v_lshl_add_u64 v[218:219], s[30:31], 0, v[132:133]
	s_mov_b32 m0, s42
	s_nop 0
	global_load_lds_dwordx4 v[218:219], off
	s_waitcnt vmcnt(8)
	s_waitcnt lgkmcnt(0)
	s_barrier
	s_setprio 1
	s_waitcnt lgkmcnt(0)
	v_mfma_f32_16x16x32_bf16 v[128:131], v[142:145], v[178:181], v[128:131]
	v_mfma_f32_16x16x32_bf16 v[120:123], v[150:153], v[178:181], v[120:123]
	v_mfma_f32_16x16x32_bf16 v[112:115], v[142:145], v[186:189], v[112:115]
	v_mfma_f32_16x16x32_bf16 v[104:107], v[150:153], v[186:189], v[104:107]
	v_mfma_f32_16x16x32_bf16 v[96:99], v[142:145], v[194:197], v[96:99]
	v_mfma_f32_16x16x32_bf16 v[88:91], v[150:153], v[194:197], v[88:91]
	v_mfma_f32_16x16x32_bf16 v[80:83], v[142:145], v[202:205], v[80:83]
	v_mfma_f32_16x16x32_bf16 v[72:75], v[150:153], v[202:205], v[72:75]
	v_mfma_f32_16x16x32_bf16 v[128:131], v[146:149], v[182:185], v[128:131]
	v_mfma_f32_16x16x32_bf16 v[120:123], v[154:157], v[182:185], v[120:123]
	v_mfma_f32_16x16x32_bf16 v[112:115], v[146:149], v[190:193], v[112:115]
	v_mfma_f32_16x16x32_bf16 v[104:107], v[154:157], v[190:193], v[104:107]
	v_mfma_f32_16x16x32_bf16 v[96:99], v[146:149], v[198:201], v[96:99]
	v_mfma_f32_16x16x32_bf16 v[88:91], v[154:157], v[198:201], v[88:91]
	v_mfma_f32_16x16x32_bf16 v[80:83], v[146:149], v[206:209], v[80:83]
	v_mfma_f32_16x16x32_bf16 v[72:75], v[154:157], v[206:209], v[72:75]
	s_setprio 0
	s_setprio 1
	v_mfma_f32_16x16x32_bf16 v[124:127], v[158:161], v[178:181], v[124:127]
	v_mfma_f32_16x16x32_bf16 v[116:119], v[166:169], v[178:181], v[116:119]
	v_mfma_f32_16x16x32_bf16 v[108:111], v[158:161], v[186:189], v[108:111]
	v_mfma_f32_16x16x32_bf16 v[100:103], v[166:169], v[186:189], v[100:103]
	v_mfma_f32_16x16x32_bf16 v[92:95], v[158:161], v[194:197], v[92:95]
	v_mfma_f32_16x16x32_bf16 v[84:87], v[166:169], v[194:197], v[84:87]
	v_mfma_f32_16x16x32_bf16 v[76:79], v[158:161], v[202:205], v[76:79]
	v_mfma_f32_16x16x32_bf16 v[68:71], v[166:169], v[202:205], v[68:71]
	v_mfma_f32_16x16x32_bf16 v[124:127], v[162:165], v[182:185], v[124:127]
	v_mfma_f32_16x16x32_bf16 v[116:119], v[170:173], v[182:185], v[116:119]
	v_mfma_f32_16x16x32_bf16 v[108:111], v[162:165], v[190:193], v[108:111]
	v_mfma_f32_16x16x32_bf16 v[100:103], v[170:173], v[190:193], v[100:103]
	v_mfma_f32_16x16x32_bf16 v[92:95], v[162:165], v[198:201], v[92:95]
	v_mfma_f32_16x16x32_bf16 v[84:87], v[170:173], v[198:201], v[84:87]
	v_mfma_f32_16x16x32_bf16 v[76:79], v[162:165], v[206:209], v[76:79]
	v_mfma_f32_16x16x32_bf16 v[68:71], v[170:173], v[206:209], v[68:71]
	s_setprio 0
	s_barrier
	s_add_i32 s30, s52, s38
	v_lshl_add_u64 v[210:211], v[210:211], 0, s[84:85]
	s_mov_b32 m0, s30
	ds_read_b128 v[178:181], v177 offset:49152
	ds_read_b128 v[182:185], v177 offset:50176
	ds_read_b128 v[186:189], v177 offset:51200
	ds_read_b128 v[190:193], v177 offset:52224
	ds_read_b128 v[194:197], v177 offset:53248
	ds_read_b128 v[198:201], v177 offset:54272
	ds_read_b128 v[202:205], v177 offset:55296
	ds_read_b128 v[206:209], v177 offset:56320
	global_load_lds_dwordx4 v[210:211], off
	s_add_i32 m0, s30, 0x2000
	s_add_u32 s28, s28, 0x40080
	v_lshl_add_u64 v[210:211], v[212:213], 0, s[84:85]
	s_addc_u32 s29, s29, 0
	s_add_i32 s30, s53, s38
	global_load_lds_dwordx4 v[210:211], off
	v_lshl_add_u64 v[210:211], s[28:29], 0, v[134:135]
	s_mov_b32 m0, s30
	s_nop 0
	global_load_lds_dwordx4 v[210:211], off
	v_lshl_add_u64 v[210:211], s[28:29], 0, v[0:1]
	s_add_i32 m0, s30, 0x2000
	s_nop 0
	global_load_lds_dwordx4 v[210:211], off
	v_lshl_add_u64 v[210:211], v[214:215], 0, s[84:85]
	s_mov_b32 m0, s44
	s_nop 0
	global_load_lds_dwordx4 v[210:211], off
	v_lshl_add_u64 v[210:211], v[216:217], 0, s[84:85]
	s_mov_b32 m0, s45
	s_nop 0
	global_load_lds_dwordx4 v[210:211], off
	s_waitcnt vmcnt(8)
	s_waitcnt lgkmcnt(0)
	s_barrier
	s_setprio 1
	s_waitcnt lgkmcnt(0)
	v_mfma_f32_16x16x32_bf16 v[64:67], v[142:145], v[178:181], v[64:67]
	v_mfma_f32_16x16x32_bf16 v[56:59], v[150:153], v[178:181], v[56:59]
	v_mfma_f32_16x16x32_bf16 v[48:51], v[142:145], v[186:189], v[48:51]
	v_mfma_f32_16x16x32_bf16 v[40:43], v[150:153], v[186:189], v[40:43]
	v_mfma_f32_16x16x32_bf16 v[32:35], v[142:145], v[194:197], v[32:35]
	v_mfma_f32_16x16x32_bf16 v[24:27], v[150:153], v[194:197], v[24:27]
	v_mfma_f32_16x16x32_bf16 v[16:19], v[142:145], v[202:205], v[16:19]
	v_mfma_f32_16x16x32_bf16 v[8:11], v[150:153], v[202:205], v[8:11]
	v_mfma_f32_16x16x32_bf16 v[64:67], v[146:149], v[182:185], v[64:67]
	v_mfma_f32_16x16x32_bf16 v[56:59], v[154:157], v[182:185], v[56:59]
	v_mfma_f32_16x16x32_bf16 v[48:51], v[146:149], v[190:193], v[48:51]
	v_mfma_f32_16x16x32_bf16 v[40:43], v[154:157], v[190:193], v[40:43]
	v_mfma_f32_16x16x32_bf16 v[32:35], v[146:149], v[198:201], v[32:35]
	v_mfma_f32_16x16x32_bf16 v[24:27], v[154:157], v[198:201], v[24:27]
	v_mfma_f32_16x16x32_bf16 v[16:19], v[146:149], v[206:209], v[16:19]
	v_mfma_f32_16x16x32_bf16 v[8:11], v[154:157], v[206:209], v[8:11]
	s_setprio 0
	s_setprio 1
	v_mfma_f32_16x16x32_bf16 v[60:63], v[158:161], v[178:181], v[60:63]
	v_mfma_f32_16x16x32_bf16 v[52:55], v[166:169], v[178:181], v[52:55]
	v_mfma_f32_16x16x32_bf16 v[44:47], v[158:161], v[186:189], v[44:47]
	v_mfma_f32_16x16x32_bf16 v[36:39], v[166:169], v[186:189], v[36:39]
	v_mfma_f32_16x16x32_bf16 v[28:31], v[158:161], v[194:197], v[28:31]
	v_mfma_f32_16x16x32_bf16 v[20:23], v[166:169], v[194:197], v[20:23]
	v_mfma_f32_16x16x32_bf16 v[12:15], v[158:161], v[202:205], v[12:15]
	v_mfma_f32_16x16x32_bf16 v[4:7], v[166:169], v[202:205], v[4:7]
	v_mfma_f32_16x16x32_bf16 v[60:63], v[162:165], v[182:185], v[60:63]
	v_mfma_f32_16x16x32_bf16 v[52:55], v[170:173], v[182:185], v[52:55]
	v_mfma_f32_16x16x32_bf16 v[44:47], v[162:165], v[190:193], v[44:47]
	v_mfma_f32_16x16x32_bf16 v[36:39], v[170:173], v[190:193], v[36:39]
	v_mfma_f32_16x16x32_bf16 v[28:31], v[162:165], v[198:201], v[28:31]
	v_mfma_f32_16x16x32_bf16 v[20:23], v[170:173], v[198:201], v[20:23]
	v_mfma_f32_16x16x32_bf16 v[12:15], v[162:165], v[206:209], v[12:15]
	v_mfma_f32_16x16x32_bf16 v[4:7], v[170:173], v[206:209], v[4:7]
	s_setprio 0
	s_barrier
	s_add_i32 s51, s51, 2
	s_add_u32 s0, s0, 0x100
	s_addc_u32 s1, s1, 0
	s_add_u32 s49, s49, 0x100
	s_addc_u32 s50, s50, 0
	s_cmp_gt_u32 s51, 13
	s_cbranch_scc0 .LBB0_446
	s_and_b64 vcc, exec, s[18:19]
	s_cbranch_vccz .LBB0_449
	s_barrier

.LBB0_620:
	s_add_i32 s58, s34, 2
	s_add_u32 s59, s22, s30
	s_addc_u32 s35, s23, s31
	s_add_u32 s60, s0, s30
	s_addc_u32 s61, s1, s31
	s_add_i32 s62, 16, 0x10000
	s_cmp_eq_u32 s54, s34
	s_cselect_b32 s35, s9, s35
	s_cselect_b32 s34, s8, s59
	v_add_u32_e32 v149, s62, v147
	s_cselect_b32 s61, s29, s61
	s_cselect_b32 s60, s28, s60
	s_add_i32 s59, 16, 0x14000
	ds_read_b128 v[150:153], v149
	ds_read_b128 v[154:157], v149 offset:1024
	ds_read_b128 v[158:161], v149 offset:2048
	ds_read_b128 v[162:165], v149 offset:3072
	v_add_u32_e32 v149, s59, v147
	ds_read_b128 v[166:169], v149
	ds_read_b128 v[170:173], v149 offset:1024
	ds_read_b128 v[174:177], v149 offset:2048
	ds_read_b128 v[178:181], v149 offset:3072
	v_lshl_add_u64 v[214:215], s[22:23], 0, v[144:145]
	s_add_i32 m0, s47, 0xc000
	ds_read_b128 v[182:185], v148
	ds_read_b128 v[186:189], v148 offset:1024
	ds_read_b128 v[190:193], v148 offset:2048
	ds_read_b128 v[194:197], v148 offset:3072
	ds_read_b128 v[198:201], v148 offset:4096
	ds_read_b128 v[202:205], v148 offset:5120
	ds_read_b128 v[206:209], v148 offset:6144
	ds_read_b128 v[210:213], v148 offset:7168
	global_load_lds_dwordx4 v[214:215], off
	v_lshl_add_u64 v[214:215], s[22:23], 0, v[142:143]
	s_add_i32 m0, s47, 0xe000
	s_nop 0
	global_load_lds_dwordx4 v[214:215], off
	s_waitcnt vmcnt(8)
	s_waitcnt lgkmcnt(0)
	s_barrier
	s_setprio 1
	s_waitcnt lgkmcnt(0)
	v_mfma_f32_16x16x32_bf16 v[128:131], v[150:153], v[182:185], v[128:131]
	v_mfma_f32_16x16x32_bf16 v[124:127], v[158:161], v[182:185], v[124:127]
	v_mfma_f32_16x16x32_bf16 v[120:123], v[150:153], v[190:193], v[120:123]
	v_mfma_f32_16x16x32_bf16 v[116:119], v[158:161], v[190:193], v[116:119]
	v_mfma_f32_16x16x32_bf16 v[112:115], v[150:153], v[198:201], v[112:115]
	v_mfma_f32_16x16x32_bf16 v[108:111], v[158:161], v[198:201], v[108:111]
	v_mfma_f32_16x16x32_bf16 v[104:107], v[150:153], v[206:209], v[104:107]
	v_mfma_f32_16x16x32_bf16 v[100:103], v[158:161], v[206:209], v[100:103]
	v_mfma_f32_16x16x32_bf16 v[128:131], v[154:157], v[186:189], v[128:131]
	v_mfma_f32_16x16x32_bf16 v[124:127], v[162:165], v[186:189], v[124:127]
	v_mfma_f32_16x16x32_bf16 v[120:123], v[154:157], v[194:197], v[120:123]
	v_mfma_f32_16x16x32_bf16 v[116:119], v[162:165], v[194:197], v[116:119]
	v_mfma_f32_16x16x32_bf16 v[112:115], v[154:157], v[202:205], v[112:115]
	v_mfma_f32_16x16x32_bf16 v[108:111], v[162:165], v[202:205], v[108:111]
	v_mfma_f32_16x16x32_bf16 v[104:107], v[154:157], v[210:213], v[104:107]
	v_mfma_f32_16x16x32_bf16 v[100:103], v[162:165], v[210:213], v[100:103]
	s_setprio 0
	s_setprio 1
	v_mfma_f32_16x16x32_bf16 v[64:67], v[166:169], v[182:185], v[64:67]
	v_mfma_f32_16x16x32_bf16 v[60:63], v[174:177], v[182:185], v[60:63]
	v_mfma_f32_16x16x32_bf16 v[56:59], v[166:169], v[190:193], v[56:59]
	v_mfma_f32_16x16x32_bf16 v[52:55], v[174:177], v[190:193], v[52:55]
	v_mfma_f32_16x16x32_bf16 v[48:51], v[166:169], v[198:201], v[48:51]
	v_mfma_f32_16x16x32_bf16 v[44:47], v[174:177], v[198:201], v[44:47]
	v_mfma_f32_16x16x32_bf16 v[40:43], v[166:169], v[206:209], v[40:43]
	v_mfma_f32_16x16x32_bf16 v[36:39], v[174:177], v[206:209], v[36:39]
	v_mfma_f32_16x16x32_bf16 v[64:67], v[170:173], v[186:189], v[64:67]
	v_mfma_f32_16x16x32_bf16 v[60:63], v[178:181], v[186:189], v[60:63]
	v_mfma_f32_16x16x32_bf16 v[56:59], v[170:173], v[194:197], v[56:59]
	v_mfma_f32_16x16x32_bf16 v[52:55], v[178:181], v[194:197], v[52:55]
	v_mfma_f32_16x16x32_bf16 v[48:51], v[170:173], v[202:205], v[48:51]
	v_mfma_f32_16x16x32_bf16 v[44:47], v[178:181], v[202:205], v[44:47]
	v_mfma_f32_16x16x32_bf16 v[40:43], v[170:173], v[210:213], v[40:43]
	v_mfma_f32_16x16x32_bf16 v[36:39], v[178:181], v[210:213], v[36:39]
	s_setprio 0
	s_barrier
	s_add_i32 s62, s62, s42
	v_lshl_add_u64 v[214:215], s[60:61], 0, v[134:135]
	s_mov_b32 m0, s62
	ds_read_b128 v[182:185], v148 offset:16384
	ds_read_b128 v[186:189], v148 offset:17408
	ds_read_b128 v[190:193], v148 offset:18432
	ds_read_b128 v[194:197], v148 offset:19456
	ds_read_b128 v[198:201], v148 offset:20480
	ds_read_b128 v[202:205], v148 offset:21504
	ds_read_b128 v[206:209], v148 offset:22528
	ds_read_b128 v[210:213], v148 offset:23552
	global_load_lds_dwordx4 v[214:215], off
	s_add_i32 m0, s62, 0x2000
	v_lshl_add_u64 v[216:217], s[60:61], 0, v[0:1]
	s_add_u32 s60, s60, s40
	s_addc_u32 s61, s61, 0
	s_add_i32 s59, s59, s42
	global_load_lds_dwordx4 v[216:217], off
	v_lshl_add_u64 v[218:219], s[60:61], 0, v[134:135]
	s_mov_b32 m0, s59
	v_lshl_add_u64 v[220:221], s[60:61], 0, v[0:1]
	global_load_lds_dwordx4 v[218:219], off
	s_add_i32 m0, s59, 0x2000
	v_lshl_add_u64 v[224:225], s[34:35], 0, v[136:137]
	global_load_lds_dwordx4 v[220:221], off
	v_lshl_add_u64 v[226:227], s[34:35], 0, v[132:133]
	s_waitcnt vmcnt(6)
	s_waitcnt lgkmcnt(0)
	s_barrier
	s_setprio 1
	s_waitcnt lgkmcnt(0)
	v_mfma_f32_16x16x32_bf16 v[96:99], v[150:153], v[182:185], v[96:99]
	v_mfma_f32_16x16x32_bf16 v[92:95], v[158:161], v[182:185], v[92:95]
	v_mfma_f32_16x16x32_bf16 v[88:91], v[150:153], v[190:193], v[88:91]
	v_mfma_f32_16x16x32_bf16 v[84:87], v[158:161], v[190:193], v[84:87]
	v_mfma_f32_16x16x32_bf16 v[80:83], v[150:153], v[198:201], v[80:83]
	v_mfma_f32_16x16x32_bf16 v[76:79], v[158:161], v[198:201], v[76:79]
	v_mfma_f32_16x16x32_bf16 v[72:75], v[150:153], v[206:209], v[72:75]
	v_mfma_f32_16x16x32_bf16 v[68:71], v[158:161], v[206:209], v[68:71]
	v_mfma_f32_16x16x32_bf16 v[96:99], v[154:157], v[186:189], v[96:99]
	v_mfma_f32_16x16x32_bf16 v[92:95], v[162:165], v[186:189], v[92:95]
	v_mfma_f32_16x16x32_bf16 v[88:91], v[154:157], v[194:197], v[88:91]
	v_mfma_f32_16x16x32_bf16 v[84:87], v[162:165], v[194:197], v[84:87]
	v_mfma_f32_16x16x32_bf16 v[80:83], v[154:157], v[202:205], v[80:83]
	v_mfma_f32_16x16x32_bf16 v[76:79], v[162:165], v[202:205], v[76:79]
	v_mfma_f32_16x16x32_bf16 v[72:75], v[154:157], v[210:213], v[72:75]
	v_mfma_f32_16x16x32_bf16 v[68:71], v[162:165], v[210:213], v[68:71]
	s_setprio 0
	s_setprio 1
	v_mfma_f32_16x16x32_bf16 v[32:35], v[166:169], v[182:185], v[32:35]
	v_mfma_f32_16x16x32_bf16 v[28:31], v[174:177], v[182:185], v[28:31]
	v_mfma_f32_16x16x32_bf16 v[24:27], v[166:169], v[190:193], v[24:27]
	v_mfma_f32_16x16x32_bf16 v[20:23], v[174:177], v[190:193], v[20:23]
	v_mfma_f32_16x16x32_bf16 v[16:19], v[166:169], v[198:201], v[16:19]
	v_mfma_f32_16x16x32_bf16 v[12:15], v[174:177], v[198:201], v[12:15]
	v_mfma_f32_16x16x32_bf16 v[8:11], v[166:169], v[206:209], v[8:11]
	v_mfma_f32_16x16x32_bf16 v[4:7], v[174:177], v[206:209], v[4:7]
	v_mfma_f32_16x16x32_bf16 v[32:35], v[170:173], v[186:189], v[32:35]
	v_mfma_f32_16x16x32_bf16 v[28:31], v[178:181], v[186:189], v[28:31]
	v_mfma_f32_16x16x32_bf16 v[24:27], v[170:173], v[194:197], v[24:27]
	v_mfma_f32_16x16x32_bf16 v[20:23], v[178:181], v[194:197], v[20:23]
	v_mfma_f32_16x16x32_bf16 v[16:19], v[170:173], v[202:205], v[16:19]
	v_mfma_f32_16x16x32_bf16 v[12:15], v[178:181], v[202:205], v[12:15]
	v_mfma_f32_16x16x32_bf16 v[8:11], v[170:173], v[210:213], v[8:11]
	v_mfma_f32_16x16x32_bf16 v[4:7], v[178:181], v[210:213], v[4:7]
	s_setprio 0
	s_barrier
	s_add_i32 s59, 16, 0x18000
	v_add_u32_e32 v149, s59, v147
	s_add_i32 s60, 16, 0x1c000
	ds_read_b128 v[150:153], v149
	ds_read_b128 v[154:157], v149 offset:1024
	ds_read_b128 v[158:161], v149 offset:2048
	ds_read_b128 v[162:165], v149 offset:3072
	v_add_u32_e32 v149, s60, v147
	ds_read_b128 v[166:169], v149
	ds_read_b128 v[170:173], v149 offset:1024
	ds_read_b128 v[174:177], v149 offset:2048
	ds_read_b128 v[178:181], v149 offset:3072
	s_mov_b32 m0, s47
	s_nop 0
	global_load_lds_dwordx4 v[224:225], off
	s_mov_b32 m0, s48
	s_nop 0
	global_load_lds_dwordx4 v[226:227], off
	s_add_u32 s34, s34, s40
	s_addc_u32 s35, s35, 0
	s_mov_b32 m0, s49
	v_lshl_add_u64 v[228:229], s[34:35], 0, v[136:137]
	ds_read_b128 v[182:185], v148 offset:32768
	ds_read_b128 v[186:189], v148 offset:33792
	ds_read_b128 v[190:193], v148 offset:34816
	ds_read_b128 v[194:197], v148 offset:35840
	ds_read_b128 v[198:201], v148 offset:36864
	ds_read_b128 v[202:205], v148 offset:37888
	ds_read_b128 v[206:209], v148 offset:38912
	ds_read_b128 v[210:213], v148 offset:39936
	global_load_lds_dwordx4 v[228:229], off
	v_lshl_add_u64 v[228:229], s[34:35], 0, v[132:133]
	s_mov_b32 m0, s50
	s_nop 0
	global_load_lds_dwordx4 v[228:229], off
	s_waitcnt vmcnt(8)
	s_waitcnt lgkmcnt(0)
	s_barrier
	s_setprio 1
	s_waitcnt lgkmcnt(0)
	v_mfma_f32_16x16x32_bf16 v[128:131], v[150:153], v[182:185], v[128:131]
	v_mfma_f32_16x16x32_bf16 v[124:127], v[158:161], v[182:185], v[124:127]
	v_mfma_f32_16x16x32_bf16 v[120:123], v[150:153], v[190:193], v[120:123]
	v_mfma_f32_16x16x32_bf16 v[116:119], v[158:161], v[190:193], v[116:119]
	v_mfma_f32_16x16x32_bf16 v[112:115], v[150:153], v[198:201], v[112:115]
	v_mfma_f32_16x16x32_bf16 v[108:111], v[158:161], v[198:201], v[108:111]
	v_mfma_f32_16x16x32_bf16 v[104:107], v[150:153], v[206:209], v[104:107]
	v_mfma_f32_16x16x32_bf16 v[100:103], v[158:161], v[206:209], v[100:103]
	v_mfma_f32_16x16x32_bf16 v[128:131], v[154:157], v[186:189], v[128:131]
	v_mfma_f32_16x16x32_bf16 v[124:127], v[162:165], v[186:189], v[124:127]
	v_mfma_f32_16x16x32_bf16 v[120:123], v[154:157], v[194:197], v[120:123]
	v_mfma_f32_16x16x32_bf16 v[116:119], v[162:165], v[194:197], v[116:119]
	v_mfma_f32_16x16x32_bf16 v[112:115], v[154:157], v[202:205], v[112:115]
	v_mfma_f32_16x16x32_bf16 v[108:111], v[162:165], v[202:205], v[108:111]
	v_mfma_f32_16x16x32_bf16 v[104:107], v[154:157], v[210:213], v[104:107]
	v_mfma_f32_16x16x32_bf16 v[100:103], v[162:165], v[210:213], v[100:103]
	s_setprio 0
	s_setprio 1
	v_mfma_f32_16x16x32_bf16 v[64:67], v[166:169], v[182:185], v[64:67]
	v_mfma_f32_16x16x32_bf16 v[60:63], v[174:177], v[182:185], v[60:63]
	v_mfma_f32_16x16x32_bf16 v[56:59], v[166:169], v[190:193], v[56:59]
	v_mfma_f32_16x16x32_bf16 v[52:55], v[174:177], v[190:193], v[52:55]
	v_mfma_f32_16x16x32_bf16 v[48:51], v[166:169], v[198:201], v[48:51]
	v_mfma_f32_16x16x32_bf16 v[44:47], v[174:177], v[198:201], v[44:47]
	v_mfma_f32_16x16x32_bf16 v[40:43], v[166:169], v[206:209], v[40:43]
	v_mfma_f32_16x16x32_bf16 v[36:39], v[174:177], v[206:209], v[36:39]
	v_mfma_f32_16x16x32_bf16 v[64:67], v[170:173], v[186:189], v[64:67]
	v_mfma_f32_16x16x32_bf16 v[60:63], v[178:181], v[186:189], v[60:63]
	v_mfma_f32_16x16x32_bf16 v[56:59], v[170:173], v[194:197], v[56:59]
	v_mfma_f32_16x16x32_bf16 v[52:55], v[178:181], v[194:197], v[52:55]
	v_mfma_f32_16x16x32_bf16 v[48:51], v[170:173], v[202:205], v[48:51]
	v_mfma_f32_16x16x32_bf16 v[44:47], v[178:181], v[202:205], v[44:47]
	v_mfma_f32_16x16x32_bf16 v[40:43], v[170:173], v[210:213], v[40:43]
	v_mfma_f32_16x16x32_bf16 v[36:39], v[178:181], v[210:213], v[36:39]
	s_setprio 0
	s_barrier
	s_add_i32 s34, s59, s42
	v_lshl_add_u64 v[214:215], v[214:215], 0, s[84:85]
	s_mov_b32 m0, s34
	ds_read_b128 v[182:185], v148 offset:49152
	ds_read_b128 v[186:189], v148 offset:50176
	ds_read_b128 v[190:193], v148 offset:51200
	ds_read_b128 v[194:197], v148 offset:52224
	ds_read_b128 v[198:201], v148 offset:53248
	ds_read_b128 v[202:205], v148 offset:54272
	ds_read_b128 v[206:209], v148 offset:55296
	ds_read_b128 v[210:213], v148 offset:56320
	global_load_lds_dwordx4 v[214:215], off
	v_lshl_add_u64 v[214:215], v[216:217], 0, s[84:85]
	s_add_i32 m0, s34, 0x2000
	s_add_i32 s34, s60, s42
	global_load_lds_dwordx4 v[214:215], off
	v_lshl_add_u64 v[214:215], v[218:219], 0, s[84:85]
	s_mov_b32 m0, s34
	s_nop 0
	global_load_lds_dwordx4 v[214:215], off
	v_lshl_add_u64 v[214:215], v[220:221], 0, s[84:85]
	s_add_i32 m0, s34, 0x2000
	s_nop 0
	global_load_lds_dwordx4 v[214:215], off
	v_lshl_add_u64 v[214:215], v[224:225], 0, s[84:85]
	s_mov_b32 m0, s52
	s_nop 0
	global_load_lds_dwordx4 v[214:215], off
	v_lshl_add_u64 v[214:215], v[226:227], 0, s[84:85]
	s_mov_b32 m0, s53
	s_nop 0
	global_load_lds_dwordx4 v[214:215], off
	s_waitcnt vmcnt(8)
	s_waitcnt lgkmcnt(0)
	s_barrier
	s_setprio 1
	s_waitcnt lgkmcnt(0)
	v_mfma_f32_16x16x32_bf16 v[96:99], v[150:153], v[182:185], v[96:99]
	v_mfma_f32_16x16x32_bf16 v[92:95], v[158:161], v[182:185], v[92:95]
	v_mfma_f32_16x16x32_bf16 v[88:91], v[150:153], v[190:193], v[88:91]
	v_mfma_f32_16x16x32_bf16 v[84:87], v[158:161], v[190:193], v[84:87]
	v_mfma_f32_16x16x32_bf16 v[80:83], v[150:153], v[198:201], v[80:83]
	v_mfma_f32_16x16x32_bf16 v[76:79], v[158:161], v[198:201], v[76:79]
	v_mfma_f32_16x16x32_bf16 v[72:75], v[150:153], v[206:209], v[72:75]
	v_mfma_f32_16x16x32_bf16 v[68:71], v[158:161], v[206:209], v[68:71]
	v_mfma_f32_16x16x32_bf16 v[96:99], v[154:157], v[186:189], v[96:99]
	v_mfma_f32_16x16x32_bf16 v[92:95], v[162:165], v[186:189], v[92:95]
	v_mfma_f32_16x16x32_bf16 v[88:91], v[154:157], v[194:197], v[88:91]
	v_mfma_f32_16x16x32_bf16 v[84:87], v[162:165], v[194:197], v[84:87]
	v_mfma_f32_16x16x32_bf16 v[80:83], v[154:157], v[202:205], v[80:83]
	v_mfma_f32_16x16x32_bf16 v[76:79], v[162:165], v[202:205], v[76:79]
	v_mfma_f32_16x16x32_bf16 v[72:75], v[154:157], v[210:213], v[72:75]
	v_mfma_f32_16x16x32_bf16 v[68:71], v[162:165], v[210:213], v[68:71]
	s_setprio 0
	s_setprio 1
	v_mfma_f32_16x16x32_bf16 v[32:35], v[166:169], v[182:185], v[32:35]
	v_mfma_f32_16x16x32_bf16 v[28:31], v[174:177], v[182:185], v[28:31]
	v_mfma_f32_16x16x32_bf16 v[24:27], v[166:169], v[190:193], v[24:27]
	v_mfma_f32_16x16x32_bf16 v[20:23], v[174:177], v[190:193], v[20:23]
	v_mfma_f32_16x16x32_bf16 v[16:19], v[166:169], v[198:201], v[16:19]
	v_mfma_f32_16x16x32_bf16 v[12:15], v[174:177], v[198:201], v[12:15]
	v_mfma_f32_16x16x32_bf16 v[8:11], v[166:169], v[206:209], v[8:11]
	v_mfma_f32_16x16x32_bf16 v[4:7], v[174:177], v[206:209], v[4:7]
	v_mfma_f32_16x16x32_bf16 v[32:35], v[170:173], v[186:189], v[32:35]
	v_mfma_f32_16x16x32_bf16 v[28:31], v[178:181], v[186:189], v[28:31]
	v_mfma_f32_16x16x32_bf16 v[24:27], v[170:173], v[194:197], v[24:27]
	v_mfma_f32_16x16x32_bf16 v[20:23], v[178:181], v[194:197], v[20:23]
	v_mfma_f32_16x16x32_bf16 v[16:19], v[170:173], v[202:205], v[16:19]
	v_mfma_f32_16x16x32_bf16 v[12:15], v[178:181], v[202:205], v[12:15]
	v_mfma_f32_16x16x32_bf16 v[8:11], v[170:173], v[210:213], v[8:11]
	v_mfma_f32_16x16x32_bf16 v[4:7], v[178:181], v[210:213], v[4:7]
	s_setprio 0
	s_barrier
	s_add_u32 s30, s30, 0x100
	s_addc_u32 s31, s31, 0
	v_lshl_add_u64 v[144:145], v[144:145], 0, s[86:87]
	v_lshl_add_u64 v[142:143], v[142:143], 0, s[86:87]
	s_cmp_ge_u32 s58, s51
	s_mov_b32 s34, s58
	s_cbranch_scc0 .LBB0_620
	s_and_b64 vcc, exec, s[26:27]
	s_cbranch_vccnz .LBB0_623
	s_and_b64 vcc, exec, s[6:7]
	s_cbranch_vccnz .LBB0_608
	s_branch .LBB0_624
